# v11 + scan state stores: 4x 4-byte stores per step -> one dwordx4 after permlane32/16_swap 4x4 transpose (+3 one-lane dummy stores to keep vmcnt order)
# speedup vs baseline: 1.0528x; 1.0081x over previous
; #define LAS __attribute__((address_space(3)))
; #define LBAR() asm volatile("s_waitcnt lgkmcnt(0)\n\ts_barrier" ::: "memory")
; __device__ __forceinline__ void scan_unit(const Params& P, LAS unsigned char* lds, int vs, int h, int dir, int dvh, int tid, int lane, int wave) {
;     const bf16_t* KR = (const bf16_t*)(P.ws + OFF_PROJ) + 5 * SEC_STRIDE; const bf16_t* VR = (const bf16_t*)(P.ws + OFF_PROJ) + 6 * SEC_STRIDE;
;     bf16_t* ST = (bf16_t*)(P.ws + OFF_ST); bf16_t* FIN = (bf16_t*)(P.ws + OFF_FIN);
;     const int cbase = vs * 32;
;     const float lg2 = -__expf((dir ? P.dec_b : P.dec_f)[h]) * LOG2E;
;     const float cd = exp2f(lg2 * 128.f);
;     const int g = lane >> 4, l15 = lane & 15, q = l15 >> 2, p = lane & 3;
;     const int dkt0 = 2 * (wave >> 1), dvt0 = 2 * (wave & 1);
;     f32x4 acc[2][2];
; #pragma unroll
;     for (int a = 0; a < 2; ++a)
; #pragma unroll
;         for (int b = 0; b < 2; ++b) acc[a][b] = (f32x4){0.f, 0.f, 0.f, 0.f};
;     u32x4 kA[4], vA[2], kB[4], vB[2];
;     ...
;     SC_LOAD(kA, vA, CH(0)); SC_LOAD(kB, vB, CH(1));
;     SC_STORE(kA, vA, 0); LBAR();
.LBB0_308:
	s_and_b64 vcc, exec, s[4:5]
	s_cbranch_vccz .LBB0_266
	s_bfe_u32 s11, s74, 0x20002
	s_ashr_i32 s10, s74, 4
	s_bfe_i32 s6, s74, 0x10001
	s_bfe_u32 s14, s74, 0x10001
	s_and_b32 s13, s74, 1
	s_lshl_b32 s7, s11, 2
	s_cmp_eq_u32 s14, 0
	s_cselect_b64 vcc, -1, 0
	s_and_b64 s[4:5], vcc, exec
	s_cselect_b32 s5, s59, s61
	s_cselect_b32 s4, s58, s60
	v_mov_b32_e32 v3, s7
	global_load_dword v3, v3, s[4:5]
	v_cndmask_b32_e32 v2, v66, v112, vcc
	v_cvt_f32_ubyte0_e32 v12, v2
	s_cselect_b32 s16, 1, 30
	s_cselect_b32 s17, 2, 29
	v_mov_b32_e32 v93, v71
	v_add_u32_e32 v155, v111, v1
	v_add_u32_e32 v156, v111, v114
	s_waitcnt vmcnt(0)
	v_mul_f32_e32 v3, 0x3fb8aa3b, v3
	v_exp_f32_e32 v3, v3
	s_nop 0
	v_mul_f32_e32 v70, 0xbfb8aa3b, v3
	v_mul_f32_e32 v2, 0x43000000, v70
	v_cmp_gt_f32_e64 s[4:5], s73, v2
	s_nop 1
	v_cndmask_b32_e64 v98, 0, v149, s[4:5]
	s_and_b64 s[4:5], s[4:5], exec
	s_cselect_b32 s15, 0xffffffc0, 0
	s_lshl_b32 s12, s10, 5
	s_and_b32 s4, s6, 31
	s_or_b32 s4, s4, s12
	s_ashr_i32 s5, s4, 31
	s_lshl_b32 s48, s11, 8
	s_lshl_b64 s[4:5], s[4:5], 7
	s_add_u32 s6, s55, s48
	s_addc_u32 s7, s64, 0
	s_lshl_b32 s18, s13, 7
	v_mov_b32_e32 v3, s5
	v_or_b32_e32 v2, s4, v78
	s_add_u32 s6, s6, s18
	v_lshl_add_u64 v[94:95], v[76:77], 0, s[48:49]
	v_mov_b32_e32 v5, s5
	v_or_b32_e32 v4, s4, v80
	v_mov_b32_e32 v7, s5
	v_or_b32_e32 v6, s4, v82
	v_mov_b32_e32 v9, s5
	v_or_b32_e32 v8, s4, v84
	v_mov_b32_e32 v11, s5
	v_or_b32_e32 v10, s4, v66
	v_lshlrev_b64 v[2:3], 10, v[2:3]
	s_addc_u32 s7, s7, 0
	v_lshlrev_b64 v[4:5], 10, v[4:5]
	v_lshlrev_b64 v[6:7], 10, v[6:7]
	v_lshlrev_b64 v[8:9], 10, v[8:9]
	v_lshlrev_b64 v[10:11], 10, v[10:11]
	v_lshl_add_u64 v[2:3], v[94:95], 0, v[2:3]
	v_lshl_add_u64 v[96:97], s[6:7], 0, v[92:93]
	v_lshl_add_u64 v[4:5], v[94:95], 0, v[4:5]
	v_lshl_add_u64 v[6:7], v[94:95], 0, v[6:7]
	v_lshl_add_u64 v[8:9], v[94:95], 0, v[8:9]
	global_load_dwordx4 v[26:29], v[2:3], off
	global_load_dwordx4 v[30:33], v[4:5], off
	global_load_dwordx4 v[34:37], v[6:7], off
	global_load_dwordx4 v[38:41], v[8:9], off
	v_lshl_add_u64 v[2:3], v[96:97], 0, v[10:11]
	global_load_dwordx4 v[42:45], v[2:3], off
	v_cndmask_b32_e32 v2, v86, v113, vcc
	v_cvt_f32_ubyte0_e32 v4, v2
	v_mov_b32_e32 v3, s5
	v_or_b32_e32 v2, s4, v86
	v_lshlrev_b64 v[2:3], 10, v[2:3]
	v_lshl_add_u64 v[2:3], v[96:97], 0, v[2:3]
	global_load_dwordx4 v[46:49], v[2:3], off
	v_mul_f32_e32 v5, v70, v12
	v_mul_f32_e32 v2, v70, v4
	v_cmp_gt_f32_e64 s[4:5], s73, v5
	v_cmp_gt_f32_e64 s[6:7], s73, v2
	v_fmac_f32_e32 v98, 0x43000000, v70
	v_cndmask_b32_e64 v3, 0, v149, s[4:5]
	v_cndmask_b32_e64 v2, 0, v149, s[6:7]
	v_fmac_f32_e32 v3, v70, v12
	v_fmac_f32_e32 v2, v70, v4
	v_exp_f32_e32 v3, v3
	v_exp_f32_e32 v2, v2
	v_cndmask_b32_e64 v4, 0, v154, s[4:5]
	s_or_b32 s4, s16, s12
	v_cndmask_b32_e64 v5, 0, v154, s[6:7]
	s_or_b32 s6, s17, s12
	s_ashr_i32 s5, s4, 31
	s_ashr_i32 s7, s6, 31
	s_lshl_b64 s[16:17], s[4:5], 7
	v_ldexp_f32 v93, v3, v4
	v_ldexp_f32 v157, v2, v5
	s_lshl_b64 s[4:5], s[6:7], 7
	v_mov_b32_e32 v3, s17
	v_or_b32_e32 v2, s16, v78
	v_mov_b32_e32 v5, s17
	v_or_b32_e32 v4, s16, v80
	v_mov_b32_e32 v7, s17
	v_or_b32_e32 v6, s16, v82
	v_mov_b32_e32 v9, s17
	v_or_b32_e32 v8, s16, v84
	v_mov_b32_e32 v11, s17
	v_or_b32_e32 v10, s16, v66
	v_mov_b32_e32 v13, s17
	v_or_b32_e32 v12, s16, v86
	v_mov_b32_e32 v15, s5
	v_or_b32_e32 v14, s4, v78
	v_mov_b32_e32 v17, s5
	v_or_b32_e32 v16, s4, v80
	v_mov_b32_e32 v19, s5
	v_or_b32_e32 v18, s4, v82
	v_mov_b32_e32 v21, s5
	v_or_b32_e32 v20, s4, v84
	v_lshlrev_b64 v[2:3], 10, v[2:3]
	v_lshlrev_b64 v[4:5], 10, v[4:5]
	v_lshlrev_b64 v[6:7], 10, v[6:7]
	v_lshlrev_b64 v[8:9], 10, v[8:9]
	v_lshlrev_b64 v[10:11], 10, v[10:11]
	v_lshlrev_b64 v[12:13], 10, v[12:13]
	v_lshlrev_b64 v[14:15], 10, v[14:15]
	v_lshlrev_b64 v[16:17], 10, v[16:17]
	v_lshlrev_b64 v[18:19], 10, v[18:19]
	v_lshlrev_b64 v[20:21], 10, v[20:21]
	v_lshl_add_u64 v[2:3], v[94:95], 0, v[2:3]
	v_lshl_add_u64 v[22:23], v[94:95], 0, v[4:5]
	v_lshl_add_u64 v[24:25], v[94:95], 0, v[6:7]
	v_lshl_add_u64 v[52:53], v[94:95], 0, v[8:9]
	v_lshl_add_u64 v[54:55], v[96:97], 0, v[10:11]
	v_lshl_add_u64 v[56:57], v[96:97], 0, v[12:13]
	v_lshl_add_u64 v[58:59], v[94:95], 0, v[14:15]
	v_lshl_add_u64 v[60:61], v[94:95], 0, v[16:17]
	v_lshl_add_u64 v[62:63], v[94:95], 0, v[18:19]
	v_lshl_add_u64 v[64:65], v[94:95], 0, v[20:21]
	global_load_dwordx4 v[2:5], v[2:3], off
	s_nop 0
	global_load_dwordx4 v[6:9], v[22:23], off
	global_load_dwordx4 v[10:13], v[24:25], off
	global_load_dwordx4 v[14:17], v[52:53], off
	global_load_dwordx4 v[18:21], v[54:55], off
	s_nop 0
	global_load_dwordx4 v[22:25], v[56:57], off
	s_waitcnt vmcnt(11)
	ds_write_b128 v150, v[26:29]
	s_waitcnt vmcnt(10)
	ds_write_b128 v151, v[30:33]
	s_waitcnt vmcnt(9)
	ds_write_b128 v152, v[34:37]
	s_waitcnt vmcnt(8)
	ds_write_b128 v153, v[38:41]
	v_mov_b32_e32 v51, s5
	s_waitcnt vmcnt(7)
	v_lshlrev_b32_e32 v26, 16, v42
	v_and_b32_e32 v27, 0xffff0000, v42
	v_lshlrev_b32_e32 v28, 16, v43
	v_and_b32_e32 v29, 0xffff0000, v43
	v_lshlrev_b32_e32 v30, 16, v44
	v_and_b32_e32 v31, 0xffff0000, v44
	v_lshlrev_b32_e32 v32, 16, v45
	v_and_b32_e32 v33, 0xffff0000, v45
	v_mul_f32_e32 v26, v93, v26
	v_mul_f32_e32 v27, v93, v27
	v_mul_f32_e32 v28, v93, v28
	v_mul_f32_e32 v29, v93, v29
	s_waitcnt vmcnt(6)
	v_lshlrev_b32_e32 v34, 16, v46
	v_and_b32_e32 v35, 0xffff0000, v46
	v_lshlrev_b32_e32 v36, 16, v47
	v_and_b32_e32 v37, 0xffff0000, v47
	v_lshlrev_b32_e32 v38, 16, v48
	v_and_b32_e32 v39, 0xffff0000, v48
	v_lshlrev_b32_e32 v40, 16, v49
	v_and_b32_e32 v41, 0xffff0000, v49
	v_mul_f32_e32 v30, v93, v30
	v_mul_f32_e32 v31, v93, v31
	v_mul_f32_e32 v32, v93, v32
	v_mul_f32_e32 v33, v93, v33
	v_cvt_pk_bf16_f32 v26, v26, v27
	v_cvt_pk_bf16_f32 v27, v28, v29
	v_cvt_pk_bf16_f32 v28, v30, v31
	v_cvt_pk_bf16_f32 v29, v32, v33
	v_mul_f32_e32 v34, v157, v34
	v_mul_f32_e32 v35, v157, v35
	v_mul_f32_e32 v36, v157, v36
	v_mul_f32_e32 v37, v157, v37
	v_mul_f32_e32 v38, v157, v38
	v_mul_f32_e32 v39, v157, v39
	v_mul_f32_e32 v40, v157, v40
	v_mul_f32_e32 v41, v157, v41
	ds_write_b128 v155, v[26:29] offset:32768
	v_cvt_pk_bf16_f32 v26, v34, v35
	v_cvt_pk_bf16_f32 v27, v36, v37
	v_cvt_pk_bf16_f32 v28, v38, v39
	v_cvt_pk_bf16_f32 v29, v40, v41
	ds_write_b128 v156, v[26:29] offset:32768
	v_or_b32_e32 v50, s4, v66
	s_waitcnt lgkmcnt(0)
	s_barrier
; __device__ __forceinline__ void scan_unit(const Params& P, LAS unsigned char* lds, int vs, int h, int dir, int dvh, int tid, int lane, int wave) {
;     ...
;     const float cd = exp2f(lg2 * 128.f);
;     const int g = lane >> 4, l15 = lane & 15, q = l15 >> 2, p = lane & 3;
;     const int dkt0 = 2 * (wave >> 1), dvt0 = 2 * (wave & 1);
;     f32x4 acc[2][2];
; #pragma unroll
;     for (int a = 0; a < 2; ++a)
; #pragma unroll
;         for (int b = 0; b < 2; ++b) acc[a][b] = (f32x4){0.f, 0.f, 0.f, 0.f};
;     ...
;     SC_LOAD(kA, vA, CH(2));
	v_mov_b32_e32 v45, s5
	v_or_b32_e32 v44, s4, v86
	global_load_dwordx4 v[26:29], v[58:59], off
	global_load_dwordx4 v[30:33], v[60:61], off
	global_load_dwordx4 v[34:37], v[62:63], off
	global_load_dwordx4 v[38:41], v[64:65], off
	v_lshlrev_b64 v[42:43], 10, v[50:51]
	v_lshlrev_b64 v[44:45], 10, v[44:45]
	v_lshl_add_u64 v[42:43], v[96:97], 0, v[42:43]
	v_lshl_add_u64 v[46:47], v[96:97], 0, v[44:45]
	global_load_dwordx4 v[42:45], v[42:43], off
	s_nop 0
	global_load_dwordx4 v[46:49], v[46:47], off
	v_exp_f32_e32 v51, v98
	s_lshl_b32 s4, s14, 15
	v_mov_b32_e32 v50, 0
	s_add_u32 s6, s65, s4
	v_ldexp_f32 v98, v51, s15
	s_mov_b32 s5, 4
	s_addc_u32 s7, s68, 0
	v_mov_b32_e32 v100, v98
	v_mov_b32_e32 v101, v98
	v_and_b32_e32 v248, 4, v105
	v_lshlrev_b32_e32 v248, 9, v248
	v_and_b32_e32 v249, 8, v105
	v_lshl_add_u32 v248, v249, 1, v248
	v_sub_u32_e32 v248, v248, v105
	v_mov_b32_e32 v249, 0
	v_lshl_or_b32 v70, s13, 13, v116
	s_mov_b32 s13, 27
	v_mov_b32_e32 v51, v50
	v_mov_b32_e32 v52, v50
	v_mov_b32_e32 v53, v50
	v_mov_b32_e32 v54, v50
	v_mov_b32_e32 v55, v50
	v_mov_b32_e32 v56, v50
	v_mov_b32_e32 v57, v50
	v_mov_b32_e32 v62, v50
	v_mov_b32_e32 v63, v50
	v_mov_b32_e32 v64, v50
	v_mov_b32_e32 v65, v50
	v_mov_b32_e32 v58, v50
	v_mov_b32_e32 v59, v50
	v_mov_b32_e32 v60, v50
	v_mov_b32_e32 v61, v50
	s_branch .LBB0_311

.LBB0_311:
	v_add_u32_e32 v158, v117, v119
	v_add_u32_e32 v174, v123, v125
	v_add_u32_e32 v176, v124, v125
	v_add_u32_e32 v159, v118, v120
	v_add_u32_e32 v160, v117, v121
	v_add_u32_e32 v161, v118, v122
	ds_read_b64_tr_b16 v[166:167], v158
	ds_read_b64_tr_b16 v[168:169], v159
	ds_read_b64_tr_b16 v[170:171], v160
	ds_read_b64_tr_b16 v[172:173], v161
	ds_read_b64_tr_b16 v[174:175], v174 offset:32768
	ds_read_b64_tr_b16 v[176:177], v176 offset:32768
	v_add_u32_e32 v178, v123, v126
	v_add_u32_e32 v179, v124, v126
	ds_read_b64_tr_b16 v[182:183], v178 offset:32768
	ds_read_b64_tr_b16 v[184:185], v179 offset:32768
	v_mov_b32_e32 v99, v98
	v_pk_mul_f32 v[164:165], v[98:99], v[60:61]
	v_pk_mul_f32 v[162:163], v[100:101], v[58:59]
	v_add_u32_e32 v178, v129, v125
	s_add_i32 s14, s5, -4
	s_waitcnt lgkmcnt(2)
	v_mfma_f32_16x16x32_bf16 v[186:189], v[166:169], v[174:177], v[162:165]
	s_add_i32 s15, s13, 4
	v_add_u32_e32 v179, v130, v125
	s_and_b64 s[16:17], vcc, exec
	v_pk_mul_f32 v[164:165], v[98:99], v[64:65]
	v_pk_mul_f32 v[162:163], v[100:101], v[62:63]
	s_cselect_b32 s15, s14, s15
	s_add_i32 s15, s15, s12
	s_waitcnt lgkmcnt(0)
	v_mfma_f32_16x16x32_bf16 v[166:169], v[166:169], v[182:185], v[162:165]
	s_lshl_b32 s15, s15, 2
	s_or_b32 s16, s15, s11
	s_ashr_i32 s17, s16, 31
	v_pk_mul_f32 v[164:165], v[98:99], v[56:57]
	v_pk_mul_f32 v[162:163], v[100:101], v[54:55]
	s_lshl_b64 s[16:17], s[16:17], 16
	s_add_u32 s16, s6, s16
	v_mfma_f32_16x16x32_bf16 v[174:177], v[170:173], v[174:177], v[162:165]
	s_addc_u32 s17, s7, s17
	s_cmp_gt_u32 s14, 28
	s_nop 0
	v_pk_mul_f32 v[164:165], v[98:99], v[52:53]
	v_pk_mul_f32 v[162:163], v[100:101], v[50:51]
	s_nop 1
	v_mfma_f32_16x16x32_bf16 v[170:173], v[170:173], v[182:185], v[162:165]
	s_nop 2
	v_add_u32_e32 v162, v127, v119
	v_add_u32_e32 v163, v128, v120
	v_add_u32_e32 v164, v127, v121
	v_add_u32_e32 v165, v128, v122
	ds_read_b64_tr_b16 v[182:183], v162
	ds_read_b64_tr_b16 v[184:185], v163
	ds_read_b64_tr_b16 v[190:191], v164
	ds_read_b64_tr_b16 v[192:193], v165
	ds_read_b64_tr_b16 v[194:195], v178 offset:32768
	ds_read_b64_tr_b16 v[196:197], v179 offset:32768
	v_add_u32_e32 v178, v129, v126
	v_add_u32_e32 v179, v130, v126
	ds_read_b64_tr_b16 v[198:199], v178 offset:32768
	ds_read_b64_tr_b16 v[200:201], v179 offset:32768
	v_mov_b32_e32 v244, 0
	v_cvt_pk_fp8_f32 v244, v58, v59
	v_mov_b32_e32 v245, 0
	v_cvt_pk_fp8_f32 v245, v62, v63
	s_waitcnt lgkmcnt(2)
	v_mfma_f32_16x16x32_bf16 v[186:189], v[182:185], v[194:197], v[186:189]
	v_add_u32_e32 v58, v133, v125
	v_add_u32_e32 v59, v134, v125
	v_cvt_pk_fp8_f32 v244, v60, v61 op_sel:[0,0,1]
	s_waitcnt lgkmcnt(0)
	v_mfma_f32_16x16x32_bf16 v[182:185], v[182:185], v[198:201], v[166:169]
	v_cvt_pk_fp8_f32 v245, v64, v65 op_sel:[0,0,1]
	s_nop 1
	v_add_u32_e32 v166, v131, v119
	v_mfma_f32_16x16x32_bf16 v[174:177], v[190:193], v[194:197], v[174:177]
	v_add_u32_e32 v167, v132, v120
	v_add_u32_e32 v168, v131, v121
	v_add_u32_e32 v169, v132, v122
	v_mfma_f32_16x16x32_bf16 v[170:173], v[190:193], v[198:201], v[170:173]
	ds_read_b64_tr_b16 v[190:191], v166
	ds_read_b64_tr_b16 v[192:193], v167
	ds_read_b64_tr_b16 v[194:195], v168
	ds_read_b64_tr_b16 v[196:197], v169
	ds_read_b64_tr_b16 v[198:199], v58 offset:32768
	ds_read_b64_tr_b16 v[200:201], v59 offset:32768
	v_add_u32_e32 v58, v133, v126
	v_add_u32_e32 v59, v134, v126
	ds_read_b64_tr_b16 v[202:203], v58 offset:32768
	ds_read_b64_tr_b16 v[204:205], v59 offset:32768
	v_lshl_add_u64 v[58:59], s[16:17], 0, v[88:89]
	v_lshl_add_u64 v[58:59], v[58:59], 0, v[70:71]
	v_lshl_add_u64 v[242:243], v[58:59], 0, v[248:249]
	s_mov_b64 exec, 1
	global_store_dword v[242:243], v244, off
	s_mov_b64 exec, -1
	s_mov_b64 exec, 1
	global_store_dword v[242:243], v244, off
	s_mov_b64 exec, -1
	v_mov_b32_e32 v246, 0
	s_waitcnt lgkmcnt(2)
	v_mfma_f32_16x16x32_bf16 v[186:189], v[190:193], v[198:201], v[186:189]
	v_add_u32_e32 v58, v137, v125
	v_cvt_pk_fp8_f32 v246, v54, v55
	v_mov_b32_e32 v247, 0
	s_waitcnt lgkmcnt(0)
	v_mfma_f32_16x16x32_bf16 v[182:185], v[190:193], v[202:205], v[182:185]
	v_add_u32_e32 v59, v138, v125
	v_cvt_pk_fp8_f32 v247, v50, v51
	v_cvt_pk_fp8_f32 v246, v56, v57 op_sel:[0,0,1]
	v_mfma_f32_16x16x32_bf16 v[190:193], v[194:197], v[202:205], v[170:173]
	v_lshl_add_u64 v[54:55], s[16:17], 0, v[90:91]
	v_cvt_pk_fp8_f32 v247, v52, v53 op_sel:[0,0,1]
	v_lshl_add_u64 v[54:55], v[54:55], 0, v[70:71]
	v_add_u32_e32 v170, v135, v119
	v_mfma_f32_16x16x32_bf16 v[174:177], v[194:197], v[198:201], v[174:177]
	v_add_u32_e32 v171, v136, v120
	v_add_u32_e32 v172, v135, v121
	v_add_u32_e32 v173, v136, v122
	ds_read_b64_tr_b16 v[62:63], v170
	ds_read_b64_tr_b16 v[64:65], v171
	ds_read_b64_tr_b16 v[194:195], v172
	ds_read_b64_tr_b16 v[196:197], v173
	ds_read_b64_tr_b16 v[198:199], v58 offset:32768
	ds_read_b64_tr_b16 v[200:201], v59 offset:32768
	s_waitcnt lgkmcnt(0)
	v_mfma_f32_16x16x32_bf16 v[50:53], v[194:197], v[198:201], v[174:177]
	s_waitcnt vmcnt(7)
	s_nop 1
	v_lshlrev_b32_e32 v174, 16, v18
	v_and_b32_e32 v175, 0xffff0000, v18
	v_add_u32_e32 v58, v137, v126
	v_mul_f32_e32 v174, v93, v174
	v_mul_f32_e32 v175, v93, v175
	v_add_u32_e32 v59, v138, v126
	ds_read_b64_tr_b16 v[202:203], v58 offset:32768
	ds_read_b64_tr_b16 v[204:205], v59 offset:32768
	v_permlane32_swap_b32_e32 v244, v246
	v_permlane32_swap_b32_e32 v245, v247
	s_nop 1
	v_permlane16_swap_b32_e32 v244, v245
	v_permlane16_swap_b32_e32 v246, v247
	s_mov_b64 exec, 1
	global_store_dword v[242:243], v244, off
	s_mov_b64 exec, -1
	global_store_dwordx4 v[242:243], v[244:247], off
	ds_write_b128 v150, v[2:5] offset:49152
	ds_write_b128 v151, v[6:9] offset:49152
	ds_write_b128 v152, v[10:13] offset:49152
	ds_write_b128 v153, v[14:17] offset:49152
	v_cvt_pk_bf16_f32 v174, v174, v175
	v_lshlrev_b32_e32 v175, 16, v19
	v_and_b32_e32 v176, 0xffff0000, v19
	v_mul_f32_e32 v175, v93, v175
	v_mul_f32_e32 v176, v93, v176
	v_cvt_pk_bf16_f32 v175, v175, v176
	v_lshlrev_b32_e32 v176, 16, v20
	v_and_b32_e32 v177, 0xffff0000, v20
	v_mul_f32_e32 v176, v93, v176
	v_mul_f32_e32 v177, v93, v177
	v_cvt_pk_bf16_f32 v176, v176, v177
	v_lshlrev_b32_e32 v177, 16, v21
	v_and_b32_e32 v178, 0xffff0000, v21
	v_mul_f32_e32 v177, v93, v177
	v_mul_f32_e32 v178, v93, v178
	v_cvt_pk_bf16_f32 v177, v177, v178
	v_add_u32_e32 v178, v115, v1
	ds_write_b128 v178, v[174:177]
	s_waitcnt vmcnt(8)
	v_lshlrev_b32_e32 v174, 16, v22
	v_and_b32_e32 v175, 0xffff0000, v22
	v_mul_f32_e32 v174, v157, v174
	v_mul_f32_e32 v175, v157, v175
	v_cvt_pk_bf16_f32 v174, v174, v175
	v_lshlrev_b32_e32 v175, 16, v23
	v_and_b32_e32 v176, 0xffff0000, v23
	v_mul_f32_e32 v175, v157, v175
	v_mul_f32_e32 v176, v157, v176
	v_cvt_pk_bf16_f32 v175, v175, v176
	v_lshlrev_b32_e32 v176, 16, v24
	v_and_b32_e32 v177, 0xffff0000, v24
	v_mfma_f32_16x16x32_bf16 v[58:61], v[62:65], v[198:201], v[186:189]
	v_mul_f32_e32 v176, v157, v176
	v_mul_f32_e32 v177, v157, v177
	v_cvt_pk_bf16_f32 v176, v176, v177
	s_waitcnt lgkmcnt(5)
	v_mfma_f32_16x16x32_bf16 v[62:65], v[62:65], v[202:205], v[182:185]
	v_lshlrev_b32_e32 v177, 16, v25
	v_and_b32_e32 v178, 0xffff0000, v25
	v_mul_f32_e32 v177, v157, v177
	v_mfma_f32_16x16x32_bf16 v[54:57], v[194:197], v[202:205], v[190:193]
	v_mul_f32_e32 v178, v157, v178
	v_cvt_pk_bf16_f32 v177, v177, v178
	v_add_u32_e32 v178, v115, v114
	ds_write_b128 v178, v[174:177]
	s_cbranch_scc1 .LBB0_313
	s_add_i32 s15, s5, -1
	s_add_i32 s18, s13, 1
	s_and_b64 s[16:17], vcc, exec
	s_cselect_b32 s15, s15, s18
	s_add_i32 s16, s15, s12
	s_ashr_i32 s17, s16, 31
	s_lshl_b64 s[16:17], s[16:17], 7
	v_mov_b32_e32 v3, s17
	v_or_b32_e32 v2, s16, v78
	v_mov_b32_e32 v5, s17
	v_or_b32_e32 v4, s16, v80
	v_mov_b32_e32 v11, s17
	v_or_b32_e32 v10, s16, v82
	v_mov_b32_e32 v13, s17
	v_or_b32_e32 v12, s16, v84
	v_mov_b32_e32 v19, s17
	v_or_b32_e32 v18, s16, v66
	v_mov_b32_e32 v21, s17
	v_or_b32_e32 v20, s16, v86
	v_lshlrev_b64 v[2:3], 10, v[2:3]
	v_lshlrev_b64 v[4:5], 10, v[4:5]
	v_lshlrev_b64 v[10:11], 10, v[10:11]
	v_lshlrev_b64 v[12:13], 10, v[12:13]
	v_lshlrev_b64 v[18:19], 10, v[18:19]
	v_lshlrev_b64 v[20:21], 10, v[20:21]
	v_lshl_add_u64 v[2:3], v[94:95], 0, v[2:3]
	v_lshl_add_u64 v[6:7], v[94:95], 0, v[4:5]
	v_lshl_add_u64 v[10:11], v[94:95], 0, v[10:11]
	v_lshl_add_u64 v[14:15], v[94:95], 0, v[12:13]
	v_lshl_add_u64 v[18:19], v[96:97], 0, v[18:19]
	v_lshl_add_u64 v[22:23], v[96:97], 0, v[20:21]
	global_load_dwordx4 v[2:5], v[2:3], off
	s_nop 0
	global_load_dwordx4 v[6:9], v[6:7], off
	s_nop 0
	global_load_dwordx4 v[10:13], v[10:11], off
	s_nop 0
	global_load_dwordx4 v[14:17], v[14:15], off
	s_nop 0
	global_load_dwordx4 v[18:21], v[18:19], off
	s_nop 0
	global_load_dwordx4 v[22:25], v[22:23], off
.LBB0_313:
	s_waitcnt lgkmcnt(0)
	s_barrier
	v_add_u32_e32 v178, v139, v125
	ds_read_b64_tr_b16 v[182:183], v158 offset:49152
	ds_read_b64_tr_b16 v[184:185], v159 offset:49152
	ds_read_b64_tr_b16 v[158:159], v160 offset:49152
	ds_read_b64_tr_b16 v[160:161], v161 offset:49152
	v_add_u32_e32 v179, v140, v125
	ds_read_b64_tr_b16 v[186:187], v178
	ds_read_b64_tr_b16 v[188:189], v179
	v_add_u32_e32 v178, v139, v126
	v_add_u32_e32 v179, v140, v126
	ds_read_b64_tr_b16 v[190:191], v178
	ds_read_b64_tr_b16 v[192:193], v179
	v_pk_mul_f32 v[176:177], v[98:99], v[60:61]
	v_pk_mul_f32 v[174:175], v[100:101], v[58:59]
	v_pk_mul_f32 v[196:197], v[98:99], v[64:65]
	v_pk_mul_f32 v[194:195], v[100:101], v[62:63]
	s_add_i32 s15, s5, -3
	s_add_i32 s18, s13, 3
	s_waitcnt lgkmcnt(2)
	v_mfma_f32_16x16x32_bf16 v[174:177], v[182:185], v[186:189], v[174:177]
	s_and_b64 s[16:17], vcc, exec
	s_cselect_b32 s15, s15, s18
	v_add_u32_e32 v178, v142, v125
	s_waitcnt lgkmcnt(0)
	v_mfma_f32_16x16x32_bf16 v[182:185], v[182:185], v[190:193], v[194:197]
	s_add_i32 s15, s15, s12
	s_lshl_b32 s15, s15, 2
	s_or_b32 s16, s15, s11
	v_pk_mul_f32 v[196:197], v[98:99], v[52:53]
	v_pk_mul_f32 v[194:195], v[100:101], v[50:51]
	s_ashr_i32 s17, s16, 31
	s_lshl_b64 s[16:17], s[16:17], 16
	v_mfma_f32_16x16x32_bf16 v[186:189], v[158:161], v[186:189], v[194:197]
	s_add_u32 s16, s6, s16
	s_addc_u32 s17, s7, s17
	s_cmp_gt_u32 s14, 29
	v_pk_mul_f32 v[196:197], v[98:99], v[56:57]
	v_pk_mul_f32 v[194:195], v[100:101], v[54:55]
	v_add_u32_e32 v99, v141, v125
	s_nop 0
	v_mfma_f32_16x16x32_bf16 v[158:161], v[158:161], v[190:193], v[194:197]
	ds_read_b64_tr_b16 v[190:191], v162 offset:49152
	ds_read_b64_tr_b16 v[192:193], v163 offset:49152
	ds_read_b64_tr_b16 v[162:163], v164 offset:49152
	ds_read_b64_tr_b16 v[164:165], v165 offset:49152
	ds_read_b64_tr_b16 v[194:195], v99
	ds_read_b64_tr_b16 v[196:197], v178
	v_add_u32_e32 v99, v141, v126
	v_add_u32_e32 v178, v142, v126
	ds_read_b64_tr_b16 v[198:199], v99
	ds_read_b64_tr_b16 v[200:201], v178
	v_mov_b32_e32 v244, 0
	v_cvt_pk_fp8_f32 v244, v58, v59
	v_mov_b32_e32 v245, 0
	v_cvt_pk_fp8_f32 v245, v62, v63
	v_add_u32_e32 v58, v143, v125
	s_waitcnt lgkmcnt(2)
	v_mfma_f32_16x16x32_bf16 v[174:177], v[190:193], v[194:197], v[174:177]
	v_add_u32_e32 v59, v144, v125
	v_cvt_pk_fp8_f32 v244, v60, v61 op_sel:[0,0,1]
	v_cvt_pk_fp8_f32 v245, v64, v65 op_sel:[0,0,1]
	s_waitcnt lgkmcnt(0)
	v_mfma_f32_16x16x32_bf16 v[182:185], v[190:193], v[198:201], v[182:185]
	v_mfma_f32_16x16x32_bf16 v[186:189], v[162:165], v[194:197], v[186:189]
	v_mfma_f32_16x16x32_bf16 v[158:161], v[162:165], v[198:201], v[158:161]
	ds_read_b64_tr_b16 v[162:163], v166 offset:49152
	ds_read_b64_tr_b16 v[164:165], v167 offset:49152
	ds_read_b64_tr_b16 v[166:167], v168 offset:49152
	ds_read_b64_tr_b16 v[168:169], v169 offset:49152
	ds_read_b64_tr_b16 v[190:191], v58
	ds_read_b64_tr_b16 v[192:193], v59
	v_add_u32_e32 v58, v143, v126
	v_add_u32_e32 v59, v144, v126
	ds_read_b64_tr_b16 v[194:195], v58
	ds_read_b64_tr_b16 v[196:197], v59
	v_lshl_add_u64 v[58:59], s[16:17], 0, v[88:89]
	v_lshl_add_u64 v[58:59], v[58:59], 0, v[70:71]
	v_lshl_add_u64 v[242:243], v[58:59], 0, v[248:249]
	s_mov_b64 exec, 1
	global_store_dword v[242:243], v244, off
	s_mov_b64 exec, -1
	v_mov_b32_e32 v246, 0
	s_mov_b64 exec, 1
	global_store_dword v[242:243], v244, off
	s_mov_b64 exec, -1
	v_cvt_pk_fp8_f32 v246, v50, v51
	v_add_u32_e32 v50, v145, v125
	s_waitcnt lgkmcnt(2)
	v_mfma_f32_16x16x32_bf16 v[174:177], v[162:165], v[190:193], v[174:177]
	v_add_u32_e32 v51, v146, v125
	v_cvt_pk_fp8_f32 v246, v52, v53 op_sel:[0,0,1]
	s_waitcnt lgkmcnt(0)
	v_mfma_f32_16x16x32_bf16 v[162:165], v[162:165], v[194:197], v[182:185]
	v_mfma_f32_16x16x32_bf16 v[182:185], v[166:169], v[190:193], v[186:189]
	v_mfma_f32_16x16x32_bf16 v[158:161], v[166:169], v[194:197], v[158:161]
	ds_read_b64_tr_b16 v[62:63], v170 offset:49152
	ds_read_b64_tr_b16 v[64:65], v171 offset:49152
	ds_read_b64_tr_b16 v[166:167], v172 offset:49152
	ds_read_b64_tr_b16 v[168:169], v173 offset:49152
	ds_read_b64_tr_b16 v[170:171], v50
	ds_read_b64_tr_b16 v[172:173], v51
	v_add_u32_e32 v50, v145, v126
	s_waitcnt lgkmcnt(0)
	v_mfma_f32_16x16x32_bf16 v[58:61], v[62:65], v[170:173], v[174:177]
	s_nop 2
	v_mov_b32_e32 v247, 0
	v_cvt_pk_fp8_f32 v247, v54, v55
	v_add_u32_e32 v51, v146, v126
	ds_read_b64_tr_b16 v[186:187], v50
	ds_read_b64_tr_b16 v[188:189], v51
	v_lshl_add_u64 v[50:51], s[16:17], 0, v[90:91]
	v_cvt_pk_fp8_f32 v247, v56, v57 op_sel:[0,0,1]
	v_lshl_add_u64 v[50:51], v[50:51], 0, v[70:71]
	s_waitcnt lgkmcnt(0)
	v_mfma_f32_16x16x32_bf16 v[62:65], v[62:65], v[186:189], v[162:165]
	v_permlane32_swap_b32_e32 v244, v246
	v_permlane32_swap_b32_e32 v245, v247
	s_nop 1
	v_permlane16_swap_b32_e32 v244, v245
	v_permlane16_swap_b32_e32 v246, v247
	s_mov_b64 exec, 1
	global_store_dword v[242:243], v244, off
	s_mov_b64 exec, -1
	global_store_dwordx4 v[242:243], v[244:247], off
	v_mfma_f32_16x16x32_bf16 v[54:57], v[166:169], v[170:173], v[182:185]
	v_mfma_f32_16x16x32_bf16 v[50:53], v[166:169], v[186:189], v[158:161]
	s_cbranch_scc1 .LBB0_315
	s_waitcnt vmcnt(9)
	v_lshlrev_b32_e32 v99, 16, v42
	v_and_b32_e32 v158, 0xffff0000, v42
	v_mul_f32_e32 v99, v93, v99
	v_mul_f32_e32 v158, v93, v158
	ds_write_b128 v150, v[26:29]
	ds_write_b128 v151, v[30:33]
	ds_write_b128 v152, v[34:37]
	ds_write_b128 v153, v[38:41]
	v_cvt_pk_bf16_f32 v158, v99, v158
	v_lshlrev_b32_e32 v99, 16, v43
	v_and_b32_e32 v159, 0xffff0000, v43
	v_mul_f32_e32 v99, v93, v99
	v_mul_f32_e32 v159, v93, v159
	v_cvt_pk_bf16_f32 v159, v99, v159
	v_lshlrev_b32_e32 v99, 16, v44
	v_and_b32_e32 v160, 0xffff0000, v44
	v_mul_f32_e32 v99, v93, v99
	v_mul_f32_e32 v160, v93, v160
	v_cvt_pk_bf16_f32 v160, v99, v160
	v_lshlrev_b32_e32 v99, 16, v45
	v_and_b32_e32 v161, 0xffff0000, v45
	v_mul_f32_e32 v99, v93, v99
	v_mul_f32_e32 v161, v93, v161
	v_cvt_pk_bf16_f32 v161, v99, v161
	ds_write_b128 v155, v[158:161] offset:32768
	s_waitcnt vmcnt(8)
	v_lshlrev_b32_e32 v99, 16, v46
	v_and_b32_e32 v158, 0xffff0000, v46
	v_mul_f32_e32 v99, v157, v99
	v_mul_f32_e32 v158, v157, v158
	v_cvt_pk_bf16_f32 v158, v99, v158
	v_lshlrev_b32_e32 v99, 16, v47
	v_and_b32_e32 v159, 0xffff0000, v47
	v_mul_f32_e32 v99, v157, v99
	v_mul_f32_e32 v159, v157, v159
	v_cvt_pk_bf16_f32 v159, v99, v159
	v_lshlrev_b32_e32 v99, 16, v48
	v_and_b32_e32 v160, 0xffff0000, v48
	v_mul_f32_e32 v99, v157, v99
	v_mul_f32_e32 v160, v157, v160
	v_and_b32_e32 v161, 0xffff0000, v49
	v_cvt_pk_bf16_f32 v160, v99, v160
	v_lshlrev_b32_e32 v99, 16, v49
	v_mul_f32_e32 v161, v157, v161
	v_mul_f32_e32 v99, v157, v99
	v_cvt_pk_bf16_f32 v161, v99, v161
	ds_write_b128 v156, v[158:161] offset:32768
